# P0 tile loop: counted wait vmcnt(4) at the tile barrier (previous tile's four write-through stores stay in flight; first iteration still vmcnt(0))
# baseline (speedup 1.0000x reference)
.LBB0_59:
	s_lshl_b32 s11, s62, 3
	s_mov_b32 m0, s33
	s_or_b32 s33, s11, 1
	s_or_b32 s35, s11, 2
	s_or_b32 s56, s11, 3
	s_or_b32 s57, s11, 4
	s_or_b32 s59, s11, 5
	s_or_b32 s61, s11, 6
	s_or_b32 s64, s11, 7
	s_add_u32 s12, s54, 0x500000
	s_addc_u32 s13, s55, 0
	s_add_u32 s14, s54, 0x2300000
	s_addc_u32 s15, s55, 0
	s_add_u32 s38, s54, 0x1b00000
	s_addc_u32 s39, s55, 0
	s_add_u32 s42, s54, 0x1900000
	s_addc_u32 s43, s55, 0
	s_add_u32 s66, s54, 0x1500000
	s_addc_u32 s67, s55, 0
	s_add_i32 s7, s65, s11
	s_mul_i32 s69, s5, s7
	s_mul_hi_u32 s70, s4, s7
	s_add_i32 s71, s70, s69
	s_mul_i32 s70, s4, s7
	s_lshl_b64 s[70:71], s[70:71], 2
	s_add_u32 s69, s0, s70
	s_addc_u32 s71, s1, s71
	s_ashr_i32 s7, s6, 31
	s_lshl_b64 s[6:7], s[6:7], 2
	v_ashrrev_i32_e32 v89, 31, v88
	s_add_u32 s70, s69, s6
	s_addc_u32 s71, s71, s7
	v_lshlrev_b64 v[0:1], 2, v[88:89]
	s_add_i32 s69, s65, s33
	v_lshl_add_u64 v[2:3], s[70:71], 0, v[0:1]
	s_mul_i32 s70, s5, s69
	s_mul_hi_u32 s71, s4, s69
	s_add_i32 s71, s71, s70
	s_mul_i32 s70, s4, s69
	s_lshl_b64 s[70:71], s[70:71], 2
	s_add_u32 s69, s0, s70
	s_addc_u32 s71, s1, s71
	s_add_u32 s70, s69, s6
	s_addc_u32 s71, s71, s7
	global_load_lds_dwordx4 v[2:3], off nt
	v_lshl_add_u64 v[2:3], s[70:71], 0, v[0:1]
	s_add_i32 s70, s65, s35
	s_mul_i32 s71, s5, s70
	s_mul_hi_u32 s72, s4, s70
	s_mul_i32 s34, s33, 0x410
	s_add_i32 s71, s72, s71
	s_mul_i32 s70, s4, s70
	s_add_i32 s69, s34, 0
	s_lshl_b64 s[70:71], s[70:71], 2
	s_add_u32 s70, s0, s70
	s_addc_u32 s71, s1, s71
	s_add_u32 s70, s70, s6
	s_mov_b32 m0, s69
	s_addc_u32 s71, s71, s7
	global_load_lds_dwordx4 v[2:3], off nt
	v_lshl_add_u64 v[2:3], s[70:71], 0, v[0:1]
	s_add_i32 s70, s65, s56
	s_mul_i32 s71, s5, s70
	s_mul_hi_u32 s72, s4, s70
	s_add_i32 s71, s72, s71
	s_mul_i32 s70, s4, s70
	s_add_i32 m0, s69, 0x410
	s_lshl_b64 s[70:71], s[70:71], 2
	s_add_u32 s70, s0, s70
	s_addc_u32 s71, s1, s71
	s_add_u32 s70, s70, s6
	s_addc_u32 s71, s71, s7
	global_load_lds_dwordx4 v[2:3], off nt
	v_lshl_add_u64 v[2:3], s[70:71], 0, v[0:1]
	s_add_i32 s70, s65, s57
	s_mul_i32 s71, s5, s70
	s_mul_hi_u32 s72, s4, s70
	s_add_i32 s71, s72, s71
	s_mul_i32 s70, s4, s70
	s_add_i32 m0, s69, 0x820
	s_lshl_b64 s[70:71], s[70:71], 2
	s_add_u32 s70, s0, s70
	s_addc_u32 s71, s1, s71
	s_add_u32 s70, s70, s6
	s_addc_u32 s71, s71, s7
	global_load_lds_dwordx4 v[2:3], off nt
	v_lshl_add_u64 v[2:3], s[70:71], 0, v[0:1]
	s_add_i32 s70, s65, s59
	s_mul_i32 s71, s5, s70
	s_mul_hi_u32 s72, s4, s70
	s_add_i32 s71, s72, s71
	s_mul_i32 s70, s4, s70
	s_add_i32 m0, s69, 0xc30
	s_lshl_b64 s[70:71], s[70:71], 2
	s_add_u32 s70, s0, s70
	s_addc_u32 s71, s1, s71
	s_add_u32 s70, s70, s6
	s_addc_u32 s71, s71, s7
	global_load_lds_dwordx4 v[2:3], off nt
	v_lshl_add_u64 v[2:3], s[70:71], 0, v[0:1]
	s_add_i32 s70, s65, s61
	s_mul_i32 s71, s5, s70
	s_mul_hi_u32 s72, s4, s70
	s_add_i32 s71, s72, s71
	s_mul_i32 s70, s4, s70
	s_add_i32 m0, s69, 0x1040
	s_lshl_b64 s[70:71], s[70:71], 2
	s_add_u32 s70, s0, s70
	s_addc_u32 s71, s1, s71
	s_add_u32 s70, s70, s6
	s_addc_u32 s71, s71, s7
	s_add_i32 s65, s65, s64
	global_load_lds_dwordx4 v[2:3], off nt
	v_lshl_add_u64 v[2:3], s[70:71], 0, v[0:1]
	s_mul_i32 s5, s5, s65
	s_mul_hi_u32 s70, s4, s65
	s_add_i32 s5, s70, s5
	s_mul_i32 s4, s4, s65
	s_add_i32 m0, s69, 0x1450
	s_lshl_b64 s[4:5], s[4:5], 2
	s_add_u32 s0, s0, s4
	s_addc_u32 s1, s1, s5
	s_add_u32 s0, s0, s6
	s_addc_u32 s1, s1, s7
	global_load_lds_dwordx4 v[2:3], off nt
	v_lshl_add_u64 v[2:3], s[0:1], 0, v[0:1]
	s_add_i32 m0, s69, 0x1860
	v_and_b32_e32 v6, 7, v92
	global_load_lds_dwordx4 v[2:3], off nt
	v_ashrrev_i32_e32 v2, 3, v91
	v_lshlrev_b32_e32 v5, 1, v2
	v_add_u32_e32 v8, 64, v2
	v_add_u32_e32 v13, 0xc0, v2
	v_and_b32_e32 v18, 0x78, v5
	v_and_b32_e32 v7, 0x7b, v2
	v_lshrrev_b32_e32 v16, 4, v2
	v_and_b32_e32 v10, 0x7b, v8
	v_lshrrev_b32_e32 v17, 4, v8
	v_add_u32_e32 v11, 0x80, v2
	v_and_b32_e32 v15, 0x7b, v13
	v_lshrrev_b32_e32 v19, 4, v13
	s_lshl_b32 s0, s8, 2
	s_mov_b32 s65, 0
	v_lshlrev_b32_e32 v3, 4, v6
	v_bfe_u32 v4, v2, 2, 1
	v_lshlrev_b32_e32 v5, 2, v2
	v_mul_u32_u24_e32 v6, 0x2080, v6
	v_or_b32_e32 v7, 0x1000, v7
	v_lshlrev_b32_e32 v9, 2, v8
	v_or_b32_e32 v10, 0x1000, v10
	v_lshlrev_b32_e32 v12, 2, v11
	v_lshlrev_b32_e32 v14, 2, v13
	v_or_b32_e32 v15, 0x1000, v15
	v_and_or_b32 v16, v16, 4, v18
	v_and_or_b32 v17, v17, 4, v18
	v_and_or_b32 v18, v19, 4, v18
	s_add_i32 s76, s0, 0x7ffff100
	s_add_i32 s77, s68, 0x7fffd400
	s_movk_i32 s78, 0x3ff
	s_movk_i32 s79, 0xbff
	s_movk_i32 s80, 0x1c00
	s_movk_i32 s81, 0xff83
	s_mov_b32 s7, 0x20000
	s_mov_b32 s99, 0
	s_branch .LBB0_62

.LBB0_103:
.Lp0_desc_done:
	s_cmp_eq_u32 s99, 0
	s_cbranch_scc1 .Lp0_w0
	s_waitcnt vmcnt(4) lgkmcnt(0)
	s_branch .Lp0_wd

.Lp0_wd:
	s_barrier
	s_mov_b32 s99, 1
	s_cmp_lg_u32 s101, 0
	s_cbranch_scc1 .LBB0_104
	s_bitcmp1_b32 s65, 0
	s_cselect_b32 s73, 0, 0x10400
	s_add_i32 s89, s73, 0
	s_add_i32 s73, s88, s11
	s_mul_i32 s74, s71, s73
	s_mul_hi_u32 s75, s70, s73
	s_add_i32 s75, s75, s74
	s_mul_i32 s74, s70, s73
	s_lshl_b64 s[74:75], s[74:75], 2
	s_add_u32 s74, s0, s74
	s_addc_u32 s75, s1, s75
	s_ashr_i32 s73, s72, 31
	s_lshl_b64 s[72:73], s[72:73], 2
	s_add_u32 s74, s74, s72
	s_addc_u32 s75, s75, s73
	v_lshl_add_u64 v[20:21], s[74:75], 0, v[0:1]
	s_add_i32 s74, s88, s33
	s_mul_i32 s75, s71, s74
	s_mul_hi_u32 s90, s70, s74
	s_add_i32 s75, s90, s75
	s_mul_i32 s74, s70, s74
	s_add_i32 m0, s89, s3
	s_lshl_b64 s[74:75], s[74:75], 2
	s_add_u32 s74, s0, s74
	s_addc_u32 s75, s1, s75
	s_add_u32 s74, s74, s72
	s_addc_u32 s75, s75, s73
	global_load_lds_dwordx4 v[20:21], off nt
	v_lshl_add_u64 v[20:21], s[74:75], 0, v[0:1]
	s_add_i32 s74, s88, s35
	s_mul_i32 s75, s71, s74
	s_mul_hi_u32 s90, s70, s74
	s_add_i32 s75, s90, s75
	s_mul_i32 s74, s70, s74
	s_add_i32 s89, s89, s34
	s_lshl_b64 s[74:75], s[74:75], 2
	s_add_u32 s74, s0, s74
	s_addc_u32 s75, s1, s75
	s_add_u32 s74, s74, s72
	s_mov_b32 m0, s89
	s_addc_u32 s75, s75, s73
	global_load_lds_dwordx4 v[20:21], off nt
	v_lshl_add_u64 v[20:21], s[74:75], 0, v[0:1]
	s_add_i32 s74, s88, s56
	s_mul_i32 s75, s71, s74
	s_mul_hi_u32 s90, s70, s74
	s_add_i32 s75, s90, s75
	s_mul_i32 s74, s70, s74
	s_add_i32 m0, s89, 0x410
	s_lshl_b64 s[74:75], s[74:75], 2
	s_add_u32 s74, s0, s74
	s_addc_u32 s75, s1, s75
	s_add_u32 s74, s74, s72
	s_addc_u32 s75, s75, s73
	global_load_lds_dwordx4 v[20:21], off nt
	v_lshl_add_u64 v[20:21], s[74:75], 0, v[0:1]
	s_add_i32 s74, s88, s57
	s_mul_i32 s75, s71, s74
	s_mul_hi_u32 s90, s70, s74
	s_add_i32 s75, s90, s75
	s_mul_i32 s74, s70, s74
	s_add_i32 m0, s89, 0x820
	s_lshl_b64 s[74:75], s[74:75], 2
	s_add_u32 s74, s0, s74
	s_addc_u32 s75, s1, s75
	s_add_u32 s74, s74, s72
	s_addc_u32 s75, s75, s73
	global_load_lds_dwordx4 v[20:21], off nt
	v_lshl_add_u64 v[20:21], s[74:75], 0, v[0:1]
	s_add_i32 s74, s88, s59
	s_mul_i32 s75, s71, s74
	s_mul_hi_u32 s90, s70, s74
	s_add_i32 s75, s90, s75
	s_mul_i32 s74, s70, s74
	s_add_i32 m0, s89, 0xc30
	s_lshl_b64 s[74:75], s[74:75], 2
	s_add_u32 s74, s0, s74
	s_addc_u32 s75, s1, s75
	s_add_u32 s74, s74, s72
	s_addc_u32 s75, s75, s73
	global_load_lds_dwordx4 v[20:21], off nt
	v_lshl_add_u64 v[20:21], s[74:75], 0, v[0:1]
	s_add_i32 s74, s88, s61
	s_mul_i32 s75, s71, s74
	s_mul_hi_u32 s90, s70, s74
	s_add_i32 s75, s90, s75
	s_mul_i32 s74, s70, s74
	s_add_i32 m0, s89, 0x1040
	s_lshl_b64 s[74:75], s[74:75], 2
	s_add_u32 s74, s0, s74
	s_addc_u32 s75, s1, s75
	s_add_u32 s74, s74, s72
	s_addc_u32 s75, s75, s73
	global_load_lds_dwordx4 v[20:21], off nt
	v_lshl_add_u64 v[20:21], s[74:75], 0, v[0:1]
	s_add_i32 s74, s88, s64
	s_mul_i32 s71, s71, s74
	s_mul_hi_u32 s75, s70, s74
	s_add_i32 s71, s75, s71
	s_mul_i32 s70, s70, s74
	s_add_i32 m0, s89, 0x1450
	s_lshl_b64 s[70:71], s[70:71], 2
	s_add_u32 s0, s0, s70
	s_addc_u32 s1, s1, s71
	s_add_u32 s0, s0, s72
	s_addc_u32 s1, s1, s73
	global_load_lds_dwordx4 v[20:21], off nt
	v_lshl_add_u64 v[20:21], s[0:1], 0, v[0:1]
	s_add_i32 m0, s89, 0x1860
	s_nop 0
	global_load_lds_dwordx4 v[20:21], off nt
